# grid barrier: first-arriving workgroup of each XCD issues buffer_wbl2 sc1 at once so dirty L2 lines drain during the phase tail (10 barrier instances)
# baseline (speedup 1.0000x reference)
.LBB0_58:
	s_or_b64 exec, exec, s[6:7]
	v_cvt_f32_u32_e32 v6, v4
	s_waitcnt vmcnt(0)
	v_readfirstlane_b32 s6, v5
	v_sub_u32_e32 v5, 0, v4
	v_rcp_iflag_f32_e32 v6, v6
	v_add_u32_e32 v7, s6, v3
	v_mul_f32_e32 v6, 0x4f7ffffe, v6
	v_cvt_u32_f32_e32 v6, v6
	v_mul_lo_u32 v3, v5, v6
	v_mul_hi_u32 v3, v6, v3
	v_add_u32_e32 v3, v6, v3
	v_mul_hi_u32 v3, v7, v3
	v_mul_lo_u32 v5, v3, v4
	v_sub_u32_e32 v5, v7, v5
	v_add_u32_e32 v6, 1, v3
	v_cmp_ge_u32_e32 vcc, v5, v4
	s_nop 1
	v_cndmask_b32_e32 v3, v3, v6, vcc
	v_sub_u32_e32 v6, v5, v4
	v_cndmask_b32_e32 v5, v5, v6, vcc
	v_add_u32_e32 v6, 1, v3
	v_cmp_ge_u32_e32 vcc, v5, v4
	v_add_u32_e32 v5, 1, v7
	s_nop 0
	v_cndmask_b32_e32 v3, v3, v6, vcc
	v_mul_lo_u32 v6, v4, v3
	v_sub_u32_e32 v251, v5, v6
	v_cmp_eq_u32_e32 vcc, 1, v251
	s_cbranch_vccz .Lbar_nofirst_0
	buffer_wbl2 sc1
.Lbar_nofirst_0:
	v_add_u32_e32 v4, v6, v4
	v_cmp_ne_u32_e32 vcc, v5, v4
	s_and_saveexec_b64 s[6:7], vcc
	s_xor_b64 s[6:7], exec, s[6:7]
	s_cbranch_execz .LBB0_72
	s_waitcnt lgkmcnt(0)
	v_mov_b32_e32 v2, 0x2000
	global_load_dword v2, v2, s[4:5] offset:1024 sc1
	s_add_u32 s24, s4, 0x2400
	s_addc_u32 s25, s5, 0
	s_waitcnt vmcnt(0)
	v_cmp_eq_u32_e32 vcc, v2, v3
	s_and_saveexec_b64 s[20:21], vcc
	s_cbranch_execz .LBB0_71
	s_add_u32 s22, s84, 0x3880200
	s_addc_u32 s23, s85, 0
	s_mov_b32 s33, 1
	s_mov_b64 s[26:27], 0
	v_mov_b32_e32 v2, 0
	s_branch .LBB0_62

.LBB0_140:
	s_or_b64 exec, exec, s[6:7]
	v_cvt_f32_u32_e32 v6, v4
	s_waitcnt vmcnt(0)
	v_readfirstlane_b32 s4, v5
	v_sub_u32_e32 v5, 0, v4
	v_rcp_iflag_f32_e32 v6, v6
	v_add_u32_e32 v7, s4, v3
	v_mul_f32_e32 v6, 0x4f7ffffe, v6
	v_cvt_u32_f32_e32 v6, v6
	v_mul_lo_u32 v3, v5, v6
	v_mul_hi_u32 v3, v6, v3
	v_add_u32_e32 v3, v6, v3
	v_mul_hi_u32 v3, v7, v3
	v_mul_lo_u32 v5, v3, v4
	v_sub_u32_e32 v5, v7, v5
	v_add_u32_e32 v6, 1, v3
	v_cmp_ge_u32_e32 vcc, v5, v4
	s_nop 1
	v_cndmask_b32_e32 v3, v3, v6, vcc
	v_sub_u32_e32 v6, v5, v4
	v_cndmask_b32_e32 v5, v5, v6, vcc
	v_add_u32_e32 v6, 1, v3
	v_cmp_ge_u32_e32 vcc, v5, v4
	v_add_u32_e32 v5, 1, v7
	s_nop 0
	v_cndmask_b32_e32 v3, v3, v6, vcc
	v_mul_lo_u32 v6, v4, v3
	v_sub_u32_e32 v251, v5, v6
	v_cmp_eq_u32_e32 vcc, 1, v251
	s_cbranch_vccz .Lbar_nofirst_1
	buffer_wbl2 sc1
.Lbar_nofirst_1:
	v_add_u32_e32 v4, v6, v4
	v_cmp_ne_u32_e32 vcc, v5, v4
	s_and_saveexec_b64 s[4:5], vcc
	s_xor_b64 s[4:5], exec, s[4:5]
	s_cbranch_execz .LBB0_154
	s_waitcnt lgkmcnt(0)
	v_mov_b32_e32 v2, 0x2000
	global_load_dword v2, v2, s[2:3] offset:1024 sc1
	s_add_u32 s10, s2, 0x2400
	s_addc_u32 s11, s3, 0
	s_waitcnt vmcnt(0)
	v_cmp_eq_u32_e32 vcc, v2, v3
	s_and_saveexec_b64 s[6:7], vcc
	s_cbranch_execz .LBB0_153
	s_add_u32 s8, s16, 0x4200
	s_addc_u32 s9, s17, 0
	s_mov_b32 s28, 1
	s_mov_b64 s[12:13], 0
	v_mov_b32_e32 v2, 0
	s_branch .LBB0_144

.LBB0_348:
	s_or_b64 exec, exec, s[10:11]
	v_cvt_f32_u32_e32 v6, v4
	s_waitcnt vmcnt(0)
	v_readfirstlane_b32 s10, v5
	v_sub_u32_e32 v5, 0, v4
	v_rcp_iflag_f32_e32 v6, v6
	v_add_u32_e32 v7, s10, v3
	v_mul_f32_e32 v6, 0x4f7ffffe, v6
	v_cvt_u32_f32_e32 v6, v6
	v_mul_lo_u32 v3, v5, v6
	v_mul_hi_u32 v3, v6, v3
	v_add_u32_e32 v3, v6, v3
	v_mul_hi_u32 v3, v7, v3
	v_mul_lo_u32 v5, v3, v4
	v_sub_u32_e32 v5, v7, v5
	v_add_u32_e32 v6, 1, v3
	v_cmp_ge_u32_e32 vcc, v5, v4
	s_nop 1
	v_cndmask_b32_e32 v3, v3, v6, vcc
	v_sub_u32_e32 v6, v5, v4
	v_cndmask_b32_e32 v5, v5, v6, vcc
	v_add_u32_e32 v6, 1, v3
	v_cmp_ge_u32_e32 vcc, v5, v4
	v_add_u32_e32 v5, 1, v7
	s_nop 0
	v_cndmask_b32_e32 v3, v3, v6, vcc
	v_mul_lo_u32 v6, v4, v3
	v_sub_u32_e32 v251, v5, v6
	v_cmp_eq_u32_e32 vcc, 1, v251
	s_cbranch_vccz .Lbar_nofirst_3
	buffer_wbl2 sc1
.Lbar_nofirst_3:
	v_add_u32_e32 v4, v6, v4
	v_cmp_ne_u32_e32 vcc, v5, v4
	s_and_saveexec_b64 s[10:11], vcc
	s_xor_b64 s[10:11], exec, s[10:11]
	s_cbranch_execz .LBB0_362
	v_readlane_b32 s12, v241, 9
	v_readlane_b32 s13, v241, 10
	s_waitcnt lgkmcnt(0)
	s_nop 3
	global_load_dword v2, v155, s[12:13] sc1
	s_waitcnt vmcnt(0)
	v_cmp_eq_u32_e32 vcc, v2, v3
	s_and_saveexec_b64 s[12:13], vcc
	s_cbranch_execz .LBB0_361
	s_mov_b32 s28, 1
	s_mov_b64 s[36:37], 0
	s_branch .LBB0_352

.Lbar_nofirst_4:
	v_add_u32_e32 v4, v6, v4
	v_cmp_ne_u32_e32 vcc, v5, v4
	s_and_saveexec_b64 s[10:11], vcc
	s_xor_b64 s[10:11], exec, s[10:11]
	s_cbranch_execz .LBB0_441
	v_readlane_b32 s12, v241, 9
	v_readlane_b32 s13, v241, 10
	s_waitcnt lgkmcnt(0)
	s_nop 3
	global_load_dword v2, v155, s[12:13] sc1
	s_waitcnt vmcnt(0)
	v_cmp_eq_u32_e32 vcc, v2, v3
	s_and_saveexec_b64 s[12:13], vcc
	s_cbranch_execz .LBB0_440
	s_mov_b32 s28, 1
	s_mov_b64 s[38:39], 0
	s_branch .LBB0_431

.LBB0_669:
	s_or_b64 exec, exec, s[8:9]
	v_cvt_f32_u32_e32 v7, v5
	s_waitcnt vmcnt(0)
	v_readfirstlane_b32 s8, v6
	v_sub_u32_e32 v6, 0, v5
	v_rcp_iflag_f32_e32 v7, v7
	v_add_u32_e32 v8, s8, v2
	v_mul_f32_e32 v7, 0x4f7ffffe, v7
	v_cvt_u32_f32_e32 v7, v7
	v_mul_lo_u32 v2, v6, v7
	v_mul_hi_u32 v2, v7, v2
	v_add_u32_e32 v2, v7, v2
	v_mul_hi_u32 v2, v8, v2
	v_mul_lo_u32 v6, v2, v5
	v_sub_u32_e32 v6, v8, v6
	v_add_u32_e32 v7, 1, v2
	v_cmp_ge_u32_e32 vcc, v6, v5
	s_nop 1
	v_cndmask_b32_e32 v2, v2, v7, vcc
	v_sub_u32_e32 v7, v6, v5
	v_cndmask_b32_e32 v6, v6, v7, vcc
	v_add_u32_e32 v7, 1, v2
	v_cmp_ge_u32_e32 vcc, v6, v5
	v_add_u32_e32 v6, 1, v8
	s_nop 0
	v_cndmask_b32_e32 v2, v2, v7, vcc
	v_mul_lo_u32 v7, v5, v2
	v_sub_u32_e32 v251, v6, v7
	v_cmp_eq_u32_e32 vcc, 1, v251
	s_cbranch_vccz .Lbar_nofirst_6
	buffer_wbl2 sc1
.Lbar_nofirst_6:
	v_add_u32_e32 v5, v7, v5
	v_cmp_ne_u32_e32 vcc, v6, v5
	s_and_saveexec_b64 s[8:9], vcc
	s_xor_b64 s[8:9], exec, s[8:9]
	s_cbranch_execz .LBB0_683
	v_readlane_b32 s10, v241, 9
	v_readlane_b32 s11, v241, 10
	s_waitcnt lgkmcnt(0)
	s_nop 3
	global_load_dword v4, v3, s[10:11] sc1
	s_waitcnt vmcnt(0)
	v_cmp_eq_u32_e32 vcc, v4, v2
	s_and_saveexec_b64 s[10:11], vcc
	s_cbranch_execz .LBB0_682
	s_mov_b32 s20, 1
	s_mov_b64 s[12:13], 0
	s_branch .LBB0_673
